# start-up grid sync: one-lane release (every wave waits vmcnt(0), thread 0 does the L2 write-back and waits) instead of the all-wave write-back + invalidate
# speedup vs baseline: 1.0259x; 1.0005x over previous
.LBB0_3:
	s_or_b64 exec, exec, s[4:5]
	v_cmp_gt_i32_e32 vcc, 32, v2
	s_and_saveexec_b64 s[4:5], vcc
	v_lshl_add_u32 v3, v2, 2, 0
	v_add_u32_e32 v3, 0x22000, v3
	v_mov_b32_e32 v4, 0
	ds_write_b32 v3, v4
	s_or_b64 exec, exec, s[4:5]
	v_lshrrev_b32_e32 v3, 20, v0
	v_lshrrev_b32_e32 v0, 10, v0
	v_or_b32_e32 v0, v0, v3
	s_movk_i32 s4, 0x3ff
	v_and_or_b32 v0, v0, s4, v1
	v_cmp_eq_u32_e32 vcc, 0, v0
	s_waitcnt vmcnt(0) lgkmcnt(0)
	s_barrier
	s_and_saveexec_b64 s[4:5], vcc
	s_cbranch_execz .LBB0_15
	buffer_wbl2 sc1
	s_waitcnt vmcnt(0)
	s_load_dwordx2 s[2:3], s[2:3], 0x58
	v_mov_b32_e32 v4, 0
	s_mov_b64 s[6:7], exec
	v_mbcnt_lo_u32_b32 v3, s6, 0
	v_mbcnt_hi_u32_b32 v3, s7, v3
	s_waitcnt lgkmcnt(0)
	global_load_dword v0, v4, s[2:3] offset:40
	v_cmp_eq_u32_e32 vcc, 0, v3
	s_and_saveexec_b64 s[8:9], vcc
	s_cbranch_execz .LBB0_8
	s_bcnt1_i32_b64 s6, s[6:7]
	v_mov_b32_e32 v5, s6
	global_atomic_add v5, v4, v5, s[2:3] offset:32 sc0
